# c_norm (context-branch RMSNorm after the scans): the wave's 4 tokens handled together - all loads in one flight, interleaved wave reductions, gamma loaded once
# speedup vs baseline: 1.0300x; 1.0019x over previous
.LBB0_1083:
	s_or_b64 exec, exec, s[4:5]
	v_mov_b32_e32 v7, v231
	ds_read_b64 v[4:5], v229 offset:63760
	ds_read_b64 v[2:3], v229 offset:63760
	s_waitcnt lgkmcnt(0)
	ds_read_b64 v[0:1], v229 offset:63760
	v_ashrrev_i32_e32 v6, 6, v7
	s_mov_b32 s0, s76
	s_nop 0
	v_lshl_add_u32 v6, s0, 2, v6
	v_cmp_gt_i32_e32 vcc, s94, v6
	s_and_saveexec_b64 s[0:1], vcc
	s_cbranch_execz .LBB0_1088
	v_lshlrev_b32_e32 v7, 2, v7
	v_and_b32_e32 v20, 0xfc, v7
	v_lshlrev_b32_e32 v228, 2, v20
	v_lshl_add_u64 v[2:3], v[2:3], 0, v[228:229]
	s_mov_b64 s[2:3], 0xd2d4000
	v_lshl_add_u64 v[8:9], v[2:3], 0, s[2:3]
	s_waitcnt lgkmcnt(0)
	v_lshl_add_u64 v[0:1], v[0:1], 0, v[228:229]
	s_mov_b64 s[2:3], 0xdad4000
	v_lshl_add_u64 v[10:11], v[0:1], 0, s[2:3]
	v_and_b32_e32 v0, 64, v244
	v_add_u32_e32 v2, 64, v0
	v_xor_b32_e32 v0, 32, v244
	v_cmp_lt_i32_e32 vcc, v0, v2
	v_readlane_b32 s2, v255, 27
	v_xor_b32_e32 v3, 1, v244
	v_cndmask_b32_e32 v0, v244, v0, vcc
	v_lshlrev_b32_e32 v14, 2, v0
	v_xor_b32_e32 v0, 16, v244
	v_cmp_lt_i32_e32 vcc, v0, v2
	v_readlane_b32 s3, v255, 28
	s_lshl_b64 s[2:3], s[2:3], 2
	v_cndmask_b32_e32 v0, v244, v0, vcc
	v_lshlrev_b32_e32 v15, 2, v0
	v_xor_b32_e32 v0, 8, v244
	v_cmp_lt_i32_e32 vcc, v0, v2
	s_nop 1
	v_cndmask_b32_e32 v0, v244, v0, vcc
	v_lshlrev_b32_e32 v16, 2, v0
	v_xor_b32_e32 v0, 4, v244
	v_cmp_lt_i32_e32 vcc, v0, v2
	s_nop 1
	v_cndmask_b32_e32 v0, v244, v0, vcc
	v_lshlrev_b32_e32 v17, 2, v0
	v_xor_b32_e32 v0, 2, v244
	v_cmp_lt_i32_e32 vcc, v0, v2
	s_nop 1
	v_cndmask_b32_e32 v0, v244, v0, vcc
	v_lshlrev_b32_e32 v18, 2, v0
	ds_read_b64 v[0:1], v229 offset:63696
	v_cmp_lt_i32_e32 vcc, v3, v2
	s_waitcnt lgkmcnt(0)
	v_lshl_add_u64 v[0:1], v[0:1], 0, s[2:3]
	v_cndmask_b32_e32 v2, v244, v3, vcc
	v_lshlrev_b32_e32 v19, 2, v2
	v_lshl_add_u64 v[12:13], v[0:1], 0, v[228:229]
	s_mov_b64 s[2:3], 0
	v_lshlrev_b32_e32 v228, 1, v20
	s_cmp_eq_u32 s77, 0x800
	s_cbranch_scc0 .LBB0_1086
	v_ashrrev_i32_e32 v7, 31, v6
	v_lshlrev_b64 v[30:31], 10, v[6:7]
	s_mov_b64 s[2:3], 0x200000
	s_mov_b64 s[4:5], 0x400000
	v_lshl_add_u64 v[32:33], v[8:9], 0, v[30:31]
	global_load_dwordx4 v[40:43], v[32:33], off
	v_lshl_add_u64 v[32:33], v[32:33], 0, s[2:3]
	global_load_dwordx4 v[44:47], v[32:33], off
	v_lshl_add_u64 v[32:33], v[32:33], 0, s[2:3]
	global_load_dwordx4 v[48:51], v[32:33], off
	v_lshl_add_u64 v[32:33], v[32:33], 0, s[2:3]
	global_load_dwordx4 v[52:55], v[32:33], off
	v_lshl_add_u64 v[34:35], v[10:11], 0, v[30:31]
	v_lshl_add_u64 v[36:37], v[34:35], 0, 0
	global_load_dwordx4 v[56:59], v[36:37], off
	v_lshl_add_u64 v[36:37], v[36:37], 0, s[4:5]
	global_load_dwordx4 v[60:63], v[36:37], off
	v_lshl_add_u64 v[36:37], v[36:37], 0, s[4:5]
	global_load_dwordx4 v[64:67], v[36:37], off
	v_lshl_add_u64 v[34:35], v[34:35], 0, s[2:3]
	v_lshl_add_u64 v[36:37], v[34:35], 0, 0
	global_load_dwordx4 v[68:71], v[36:37], off
	v_lshl_add_u64 v[36:37], v[36:37], 0, s[4:5]
	global_load_dwordx4 v[72:75], v[36:37], off
	v_lshl_add_u64 v[36:37], v[36:37], 0, s[4:5]
	global_load_dwordx4 v[76:79], v[36:37], off
	global_load_dwordx4 v[80:83], v[12:13], off offset:2048
	s_waitcnt vmcnt(1)
	v_pk_add_f32 v[48:49], v[48:49], v[56:57]
	v_pk_add_f32 v[50:51], v[50:51], v[58:59]
	v_pk_add_f32 v[48:49], v[48:49], v[60:61]
	v_pk_add_f32 v[50:51], v[50:51], v[62:63]
	v_pk_add_f32 v[48:49], v[48:49], v[64:65]
	v_pk_add_f32 v[50:51], v[50:51], v[66:67]
	v_pk_add_f32 v[52:53], v[52:53], v[68:69]
	v_pk_add_f32 v[54:55], v[54:55], v[70:71]
	v_pk_add_f32 v[52:53], v[52:53], v[72:73]
	v_pk_add_f32 v[54:55], v[54:55], v[74:75]
	v_pk_add_f32 v[52:53], v[52:53], v[76:77]
	v_pk_add_f32 v[54:55], v[54:55], v[78:79]
	v_pk_mul_f32 v[84:85], v[40:41], v[40:41]
	v_pk_mul_f32 v[86:87], v[42:43], v[42:43]
	v_add_f32_e32 v88, v84, v85
	v_add_f32_e32 v88, v88, v86
	v_add_f32_e32 v88, v88, v87
	v_pk_mul_f32 v[84:85], v[44:45], v[44:45]
	v_pk_mul_f32 v[86:87], v[46:47], v[46:47]
	v_add_f32_e32 v89, v84, v85
	v_add_f32_e32 v89, v89, v86
	v_add_f32_e32 v89, v89, v87
	v_pk_mul_f32 v[84:85], v[48:49], v[48:49]
	v_pk_mul_f32 v[86:87], v[50:51], v[50:51]
	v_add_f32_e32 v90, v84, v85
	v_add_f32_e32 v90, v90, v86
	v_add_f32_e32 v90, v90, v87
	v_pk_mul_f32 v[84:85], v[52:53], v[52:53]
	v_pk_mul_f32 v[86:87], v[54:55], v[54:55]
	v_add_f32_e32 v91, v84, v85
	v_add_f32_e32 v91, v91, v86
	v_add_f32_e32 v91, v91, v87
	ds_bpermute_b32 v100, v14, v88
	ds_bpermute_b32 v101, v14, v89
	ds_bpermute_b32 v102, v14, v90
	ds_bpermute_b32 v103, v14, v91
	s_waitcnt lgkmcnt(0)
	v_add_f32_e32 v88, v88, v100
	v_add_f32_e32 v89, v89, v101
	v_add_f32_e32 v90, v90, v102
	v_add_f32_e32 v91, v91, v103
	ds_bpermute_b32 v100, v15, v88
	ds_bpermute_b32 v101, v15, v89
	ds_bpermute_b32 v102, v15, v90
	ds_bpermute_b32 v103, v15, v91
	s_waitcnt lgkmcnt(0)
	v_add_f32_e32 v88, v88, v100
	v_add_f32_e32 v89, v89, v101
	v_add_f32_e32 v90, v90, v102
	v_add_f32_e32 v91, v91, v103
	ds_bpermute_b32 v100, v16, v88
	ds_bpermute_b32 v101, v16, v89
	ds_bpermute_b32 v102, v16, v90
	ds_bpermute_b32 v103, v16, v91
	s_waitcnt lgkmcnt(0)
	v_add_f32_e32 v88, v88, v100
	v_add_f32_e32 v89, v89, v101
	v_add_f32_e32 v90, v90, v102
	v_add_f32_e32 v91, v91, v103
	ds_bpermute_b32 v100, v17, v88
	ds_bpermute_b32 v101, v17, v89
	ds_bpermute_b32 v102, v17, v90
	ds_bpermute_b32 v103, v17, v91
	s_waitcnt lgkmcnt(0)
	v_add_f32_e32 v88, v88, v100
	v_add_f32_e32 v89, v89, v101
	v_add_f32_e32 v90, v90, v102
	v_add_f32_e32 v91, v91, v103
	ds_bpermute_b32 v100, v18, v88
	ds_bpermute_b32 v101, v18, v89
	ds_bpermute_b32 v102, v18, v90
	ds_bpermute_b32 v103, v18, v91
	s_waitcnt lgkmcnt(0)
	v_add_f32_e32 v88, v88, v100
	v_add_f32_e32 v89, v89, v101
	v_add_f32_e32 v90, v90, v102
	v_add_f32_e32 v91, v91, v103
	ds_bpermute_b32 v100, v19, v88
	ds_bpermute_b32 v101, v19, v89
	ds_bpermute_b32 v102, v19, v90
	ds_bpermute_b32 v103, v19, v91
	s_waitcnt lgkmcnt(0)
	v_add_f32_e32 v88, v88, v100
	v_add_f32_e32 v89, v89, v101
	v_add_f32_e32 v90, v90, v102
	v_add_f32_e32 v91, v91, v103
	v_fmamk_f32 v88, v88, 0x3b800000, v230
	v_cmp_gt_f32_e32 vcc, s92, v88
	v_mul_f32_e32 v100, 0x4b800000, v88
	s_nop 0
	v_cndmask_b32_e32 v88, v88, v100, vcc
	v_rsq_f32_e32 v88, v88
	s_nop 0
	v_mul_f32_e32 v100, 0x45800000, v88
	v_cndmask_b32_e32 v92, v88, v100, vcc
	v_fmamk_f32 v89, v89, 0x3b800000, v230
	v_cmp_gt_f32_e32 vcc, s92, v89
	v_mul_f32_e32 v101, 0x4b800000, v89
	s_nop 0
	v_cndmask_b32_e32 v89, v89, v101, vcc
	v_rsq_f32_e32 v89, v89
	s_nop 0
	v_mul_f32_e32 v101, 0x45800000, v89
	v_cndmask_b32_e32 v94, v89, v101, vcc
	v_fmamk_f32 v90, v90, 0x3b800000, v230
	v_cmp_gt_f32_e32 vcc, s92, v90
	v_mul_f32_e32 v102, 0x4b800000, v90
	s_nop 0
	v_cndmask_b32_e32 v90, v90, v102, vcc
	v_rsq_f32_e32 v90, v90
	s_nop 0
	v_mul_f32_e32 v102, 0x45800000, v90
	v_cndmask_b32_e32 v96, v90, v102, vcc
	v_fmamk_f32 v91, v91, 0x3b800000, v230
	v_cmp_gt_f32_e32 vcc, s92, v91
	v_mul_f32_e32 v103, 0x4b800000, v91
	s_nop 0
	v_cndmask_b32_e32 v91, v91, v103, vcc
	v_rsq_f32_e32 v91, v91
	s_nop 0
	v_mul_f32_e32 v103, 0x45800000, v91
	v_cndmask_b32_e32 v98, v91, v103, vcc
	s_waitcnt vmcnt(0)
	v_lshlrev_b64 v[30:31], 11, v[6:7]
	v_lshl_add_u64 v[30:31], v[4:5], 0, v[30:31]
	v_lshl_add_u64 v[30:31], v[30:31], 0, v[228:229]
	s_mov_b64 s[2:3], 0x4ad4000
	v_lshl_add_u64 v[30:31], v[30:31], 0, s[2:3]
	s_mov_b64 s[2:3], 0x400000
	v_pk_mul_f32 v[40:41], v[40:41], v[92:93] op_sel_hi:[1,0]
	v_pk_mul_f32 v[42:43], v[42:43], v[92:93] op_sel_hi:[1,0]
	v_pk_mul_f32 v[40:41], v[80:81], v[40:41]
	v_pk_mul_f32 v[42:43], v[82:83], v[42:43]
	v_cvt_pk_bf16_f32 v40, v40, v41
	v_cvt_pk_bf16_f32 v41, v42, v43
	global_store_dwordx2 v[30:31], v[40:41], off offset:1024
	v_lshl_add_u64 v[30:31], v[30:31], 0, s[2:3]
	v_pk_mul_f32 v[44:45], v[44:45], v[94:95] op_sel_hi:[1,0]
	v_pk_mul_f32 v[46:47], v[46:47], v[94:95] op_sel_hi:[1,0]
	v_pk_mul_f32 v[44:45], v[80:81], v[44:45]
	v_pk_mul_f32 v[46:47], v[82:83], v[46:47]
	v_cvt_pk_bf16_f32 v44, v44, v45
	v_cvt_pk_bf16_f32 v45, v46, v47
	global_store_dwordx2 v[30:31], v[44:45], off offset:1024
	v_lshl_add_u64 v[30:31], v[30:31], 0, s[2:3]
	v_pk_mul_f32 v[48:49], v[48:49], v[96:97] op_sel_hi:[1,0]
	v_pk_mul_f32 v[50:51], v[50:51], v[96:97] op_sel_hi:[1,0]
	v_pk_mul_f32 v[48:49], v[80:81], v[48:49]
	v_pk_mul_f32 v[50:51], v[82:83], v[50:51]
	v_cvt_pk_bf16_f32 v48, v48, v49
	v_cvt_pk_bf16_f32 v49, v50, v51
	global_store_dwordx2 v[30:31], v[48:49], off offset:1024
	v_lshl_add_u64 v[30:31], v[30:31], 0, s[2:3]
	v_pk_mul_f32 v[52:53], v[52:53], v[98:99] op_sel_hi:[1,0]
	v_pk_mul_f32 v[54:55], v[54:55], v[98:99] op_sel_hi:[1,0]
	v_pk_mul_f32 v[52:53], v[80:81], v[52:53]
	v_pk_mul_f32 v[54:55], v[82:83], v[54:55]
	v_cvt_pk_bf16_f32 v52, v52, v53
	v_cvt_pk_bf16_f32 v53, v54, v55
	global_store_dwordx2 v[30:31], v[52:53], off offset:1024
	s_branch .LBB0_1088
	s_branch .LBB0_1086
